# phase 3: idle SSD-sample blocks take the 128 sixth prompt SSD items (with acquire wait on in-proj counter); sc prefetch
# baseline (speedup 1.0000x reference)
.LBB0_608:
	v_readlane_b32 s2, v254, 31
	v_readlane_b32 s3, v254, 32
	v_readlane_b32 s36, v253, 39
	s_xor_b64 s[2:3], s[2:3], -1
	v_lshl_or_b32 v2, v199, 11, v75
	v_readlane_b32 s50, v253, 53
	s_movk_i32 s24, 0xbf
	v_mov_b32_e32 v1, 0
	v_lshlrev_b32_e32 v0, 1, v198
	v_readlane_b32 s51, v253, 54
	s_add_u32 s25, s50, 0x3000000
	v_add_u32_e32 v96, v2, v197
	v_readlane_b32 s84, v253, 6
	v_readlane_b32 s82, v254, 7
	v_cmp_lt_u32_e64 s[6:7], 63, v196
	v_cmp_lt_u32_e64 s[8:9], s24, v196
	v_add_u32_e32 v103, 0x540, v196
	s_waitcnt vmcnt(9)
	v_add_u32_e32 v105, 0x3c0, v196
	v_or_b32_e32 v92, v2, v197
	v_cmp_lt_u32_e64 s[10:11], 7, v93
	s_waitcnt vmcnt(8)
	v_add_u32_e32 v107, 0x940, v79
	v_add_u32_e32 v109, 0x7c0, v79
	v_lshl_add_u64 v[94:95], s[28:29], 0, v[0:1]
	s_addc_u32 s33, s51, 0
	v_add_u32_e32 v98, v2, v73
	v_add_u32_e32 v100, v2, v71
	v_add_u32_e32 v102, v2, v69
	v_add_u32_e32 v104, 64, v96
	s_movk_i32 s54, 0x50
	v_add_u32_e32 v106, 0x50, v96
	v_add_u32_e32 v108, 0x60, v96
	v_add_u32_e32 v110, 0x70, v96
	s_mov_b32 s17, 0
	s_movk_i32 s55, 0x3880
	s_mov_b64 s[18:19], 0x1000
	s_mov_b64 s[20:21], 0x1400
	s_mov_b32 s56, 0x3fb8aa3b
	s_mov_b32 s57, 0xc2ce8ed0
	s_mov_b32 s58, 0x42b17218
	s_movk_i32 s59, 0x110
	v_mov_b32_e32 v111, 0x3ecc95a3
	s_movk_i32 s61, 0x280
	v_mov_b32_e32 v162, 0x7f800000
	v_mov_b32_e32 v112, 0x3f317218
	v_mov_b32_e32 v163, 16
	s_mov_b32 s62, s84
	s_movk_i32 s98, 0x880
	s_cmp_lt_u32 s84, 0x80
	s_cbranch_scc1 .Lssd_lim_done
	s_movk_i32 s98, 0x800
.Lssd_lim_done:
	s_add_i32 vcc_lo, s84, 0xffffffc0
	s_cmp_lt_u32 vcc_lo, 64
	s_cbranch_scc0 .Lssd_step_done
	s_movk_i32 s60, 0x7c0
.Lssd_step_done:
	v_readlane_b32 s83, v254, 8
	v_readlane_b32 s37, v253, 40
	v_readlane_b32 s38, v253, 41
	v_readlane_b32 s39, v253, 42
	v_readlane_b32 s40, v253, 43
	v_readlane_b32 s41, v253, 44
	v_readlane_b32 s42, v253, 45
	v_readlane_b32 s43, v253, 46
	v_readlane_b32 s44, v253, 47
	v_readlane_b32 s45, v253, 48
	v_readlane_b32 s46, v253, 49
	v_readlane_b32 s47, v253, 50
	v_readlane_b32 s48, v253, 51
	v_readlane_b32 s49, v253, 52
	s_branch .LBB0_610
.LBB0_609:
	s_add_i32 s62, s62, s60
	s_cmpk_ge_i32 s62, 0x800
	s_cselect_b32 s60, 64, s60
	s_cmp_lt_i32 s62, s98
	s_cbranch_scc0 .LBB0_697
	s_cmpk_lt_i32 s62, 0x800
	s_cbranch_scc1 .Lssd_nowait
	s_add_u32 s100, s88, 0xfc03600
	s_addc_u32 s101, s89, 0
	s_add_i32 s99, s92, 0xffffff80
	v_mov_b32_e32 v220, 0
.Lssd_wait:
	global_load_dword v221, v220, s[100:101] sc1
	s_waitcnt vmcnt(0)
	v_readfirstlane_b32 vcc_lo, v221
	s_nop 0
	s_cmp_ge_u32 vcc_lo, s99
	s_cbranch_scc1 .Lssd_wait_done
	s_sleep 8
	s_branch .Lssd_wait
.Lssd_wait_done:
	buffer_inv sc1
	s_waitcnt vmcnt(0)
.Lssd_nowait:
.LBB0_610:
	s_cmp_lt_i32 s62, 64
	s_cselect_b64 s[12:13], -1, 0
	s_add_i32 s14, s62, 0xffffff80
	s_cmpk_lt_u32 s14, 0x400
	s_cselect_b64 s[14:15], -1, 0
	s_or_b64 s[12:13], s[12:13], s[14:15]
	s_and_b64 vcc, exec, s[12:13]
	s_cbranch_vccnz .LBB0_609
	s_cmpk_lt_u32 s62, 0x80
	s_cselect_b64 s[12:13], -1, 0
	s_cmpk_gt_u32 s62, 0x7f
	s_mov_b64 s[14:15], -1
	s_cbranch_scc0 .LBB0_613
	s_add_i32 s16, s62, 0xfffffb80
	s_mov_b64 s[14:15], 0
